# FFN-down residual epilogue: 31 serialized x-tile loads (load/vmcnt0/fma/store chain) prefetched up front via saddr+voffset into free VGPR pairs
# speedup vs baseline: 1.0019x; 1.0019x over previous
.LBB0_118:
	s_sub_i32 s0, s86, 41
	s_cmp_lt_u32 s0, -10
	s_cselect_b64 s[20:21], -1, 0
	s_cmp_gt_u32 s0, -11
	s_cselect_b64 s[36:37], -1, 0
	s_lshl_b32 s61, s16, 8
	s_add_i32 s5, s61, s35
	s_lshl_b32 s30, s14, 8
	s_cmp_lt_i32 s16, 48
	s_cselect_b32 s0, 0x6000, s80
	s_cmp_gt_i32 s16, 31
	s_cselect_b32 s0, s0, 0
	s_lshl_b32 s0, s0, 2
	s_mul_i32 s8, s3, 0x1800
	s_add_u32 s62, s92, s0
	v_lshlrev_b32_e32 v130, 2, v156
	s_addc_u32 s63, s93, 0
	s_ashr_i32 s9, s8, 31
	v_lshl_or_b32 v130, s4, 5, v130
	s_lshl_b64 s[0:1], s[8:9], 2
	v_or_b32_e32 v152, s5, v142
	v_or_b32_e32 v146, s30, v130
	s_add_u32 s0, s62, s0
	v_ashrrev_i32_e32 v153, 31, v152
	s_addc_u32 s1, s63, s1
	v_ashrrev_i32_e32 v147, 31, v146
	v_lshlrev_b64 v[132:133], 11, v[152:153]
	v_lshl_add_u64 v[130:131], v[146:147], 2, s[0:1]
	v_lshl_add_u64 v[132:133], s[12:13], 0, v[132:133]
	s_movk_i32 s0, 0x5000
	v_lshl_add_u64 v[154:155], v[146:147], 1, v[132:133]
	v_add_co_u32_e32 v132, vcc, s0, v130
	s_mov_b64 s[0:1], 0x5000
	s_barrier
	global_load_dwordx2 v[148:149], v[154:155], off
	v_addc_co_u32_e32 v133, vcc, 0, v131, vcc
	v_lshl_add_u64 v[130:131], v[130:131], 0, s[0:1]
	global_load_dwordx4 v[142:145], v[132:133], off
	global_load_dwordx4 v[138:141], v[130:131], off offset:64
	global_load_dwordx4 v[134:137], v[130:131], off offset:512
	s_nop 0
	global_load_dwordx4 v[130:133], v[130:131], off offset:576
	v_lshlrev_b32_e32 v157, 11, v152
	v_lshl_add_u32 v157, v146, 1, v157
	global_load_dwordx2 v[158:159], v157, s[12:13] offset:32
	global_load_dwordx2 v[160:161], v157, s[12:13] offset:256
	global_load_dwordx2 v[166:167], v157, s[12:13] offset:288
	v_add_u32_e32 v157, 0x8000, v157
	global_load_dwordx2 v[170:171], v157, s[12:13]
	global_load_dwordx2 v[172:173], v157, s[12:13] offset:32
	global_load_dwordx2 v[174:175], v157, s[12:13] offset:256
	global_load_dwordx2 v[176:177], v157, s[12:13] offset:288
	v_add_u32_e32 v157, 0x8000, v157
	global_load_dwordx2 v[178:179], v157, s[12:13]
	global_load_dwordx2 v[180:181], v157, s[12:13] offset:32
	global_load_dwordx2 v[182:183], v157, s[12:13] offset:256
	global_load_dwordx2 v[184:185], v157, s[12:13] offset:288
	v_add_u32_e32 v157, 0x8000, v157
	global_load_dwordx2 v[190:191], v157, s[12:13]
	global_load_dwordx2 v[214:215], v157, s[12:13] offset:32
	global_load_dwordx2 v[216:217], v157, s[12:13] offset:256
	global_load_dwordx2 v[218:219], v157, s[12:13] offset:288
	v_add_u32_e32 v157, 0x28000, v157
	global_load_dwordx2 v[220:221], v157, s[12:13]
	global_load_dwordx2 v[222:223], v157, s[12:13] offset:32
	global_load_dwordx2 v[224:225], v157, s[12:13] offset:256
	global_load_dwordx2 v[226:227], v157, s[12:13] offset:288
	v_add_u32_e32 v157, 0x8000, v157
	global_load_dwordx2 v[228:229], v157, s[12:13]
	global_load_dwordx2 v[230:231], v157, s[12:13] offset:32
	global_load_dwordx2 v[232:233], v157, s[12:13] offset:256
	global_load_dwordx2 v[234:235], v157, s[12:13] offset:288
	v_add_u32_e32 v157, 0x8000, v157
	global_load_dwordx2 v[236:237], v157, s[12:13]
	global_load_dwordx2 v[238:239], v157, s[12:13] offset:32
	global_load_dwordx2 v[240:241], v157, s[12:13] offset:256
	global_load_dwordx2 v[242:243], v157, s[12:13] offset:288
	v_add_u32_e32 v157, 0x8000, v157
	global_load_dwordx2 v[244:245], v157, s[12:13]
	global_load_dwordx2 v[246:247], v157, s[12:13] offset:32
	global_load_dwordx2 v[248:249], v157, s[12:13] offset:256
	global_load_dwordx2 v[250:251], v157, s[12:13] offset:288
	v_readlane_b32 s40, v254, 43
	v_readlane_b32 s38, v253, 1
	s_and_b64 vcc, exec, s[20:21]
	v_readlane_b32 s41, v254, 44
	v_readlane_b32 s42, v254, 45
	v_readlane_b32 s43, v254, 46
	v_readlane_b32 s44, v254, 47
	v_readlane_b32 s45, v254, 48
	v_readlane_b32 s50, v254, 53
	v_readlane_b32 s51, v254, 54
	v_readlane_b32 s52, v254, 55
	v_readlane_b32 s53, v254, 56
	v_readlane_b32 s39, v253, 2
	v_readlane_b32 s46, v254, 49
	v_readlane_b32 s47, v254, 50
	v_readlane_b32 s48, v254, 51
	v_readlane_b32 s49, v254, 52
	v_readlane_b32 s54, v254, 57
	v_readlane_b32 s55, v254, 58
	s_waitcnt vmcnt(0)
	v_lshlrev_b32_e32 v150, 16, v148
	v_and_b32_e32 v151, 0xffff0000, v148
	v_lshlrev_b32_e32 v148, 16, v149
	v_and_b32_e32 v149, 0xffff0000, v149
	v_pk_fma_f32 v[128:129], v[128:129], v[144:145], v[148:149]
	v_pk_fma_f32 v[126:127], v[126:127], v[142:143], v[150:151]
	s_cbranch_vccz .LBB0_120
	v_cvt_pk_bf16_f32 v148, v126, v127
	v_cvt_pk_bf16_f32 v149, v128, v129
	global_store_dwordx2 v[154:155], v[148:149], off
.LBB0_120:
	v_cndmask_b32_e64 v150, 0, 1, s[20:21]
	v_cmp_ne_u32_e64 s[6:7], 1, v150
	s_andn2_b64 vcc, exec, s[20:21]
	v_lshlrev_b32_e32 v150, 16, v158
	v_and_b32_e32 v151, 0xffff0000, v158
	v_lshlrev_b32_e32 v148, 16, v159
	v_and_b32_e32 v149, 0xffff0000, v159
	v_pk_fma_f32 v[124:125], v[124:125], v[140:141], v[148:149]
	v_pk_fma_f32 v[122:123], v[122:123], v[138:139], v[150:151]
	s_cbranch_vccnz .LBB0_122
	v_cvt_pk_bf16_f32 v148, v122, v123
	v_cvt_pk_bf16_f32 v149, v124, v125
	global_store_dwordx2 v[154:155], v[148:149], off offset:32
.LBB0_122:
	s_and_b64 vcc, exec, s[6:7]
	v_lshlrev_b32_e32 v150, 16, v160
	v_and_b32_e32 v151, 0xffff0000, v160
	v_lshlrev_b32_e32 v148, 16, v161
	v_and_b32_e32 v149, 0xffff0000, v161
	v_pk_fma_f32 v[120:121], v[120:121], v[136:137], v[148:149]
	v_pk_fma_f32 v[118:119], v[118:119], v[134:135], v[150:151]
	s_cbranch_vccnz .LBB0_124
	v_cvt_pk_bf16_f32 v148, v118, v119
	v_cvt_pk_bf16_f32 v149, v120, v121
	global_store_dwordx2 v[154:155], v[148:149], off offset:256
.LBB0_124:
	s_and_b64 vcc, exec, s[6:7]
	v_lshlrev_b32_e32 v150, 16, v166
	v_and_b32_e32 v151, 0xffff0000, v166
	v_lshlrev_b32_e32 v148, 16, v167
	v_and_b32_e32 v149, 0xffff0000, v167
	v_pk_fma_f32 v[148:149], v[110:111], v[132:133], v[148:149]
	v_pk_fma_f32 v[150:151], v[108:109], v[130:131], v[150:151]
	s_cbranch_vccnz .LBB0_126
	v_cvt_pk_bf16_f32 v108, v150, v151
	v_cvt_pk_bf16_f32 v109, v148, v149
	global_store_dwordx2 v[154:155], v[108:109], off offset:288
.LBB0_126:
	v_or_b32_e32 v108, 16, v152
	v_ashrrev_i32_e32 v109, 31, v108
	v_lshlrev_b64 v[108:109], 11, v[108:109]
	v_lshl_add_u64 v[108:109], s[12:13], 0, v[108:109]
	v_lshl_add_u64 v[154:155], v[146:147], 1, v[108:109]
	s_and_b64 vcc, exec, s[6:7]
	v_lshlrev_b32_e32 v110, 16, v170
	v_and_b32_e32 v111, 0xffff0000, v170
	v_lshlrev_b32_e32 v108, 16, v171
	v_and_b32_e32 v109, 0xffff0000, v171
	v_pk_fma_f32 v[108:109], v[116:117], v[144:145], v[108:109]
	v_pk_fma_f32 v[110:111], v[114:115], v[142:143], v[110:111]
	s_cbranch_vccnz .LBB0_128
	v_cvt_pk_bf16_f32 v114, v110, v111
	v_cvt_pk_bf16_f32 v115, v108, v109
	global_store_dwordx2 v[154:155], v[114:115], off
.LBB0_128:
	s_and_b64 vcc, exec, s[6:7]
	v_lshlrev_b32_e32 v116, 16, v172
	v_and_b32_e32 v117, 0xffff0000, v172
	v_lshlrev_b32_e32 v114, 16, v173
	v_and_b32_e32 v115, 0xffff0000, v173
	v_pk_fma_f32 v[106:107], v[106:107], v[140:141], v[114:115]
	v_pk_fma_f32 v[104:105], v[104:105], v[138:139], v[116:117]
	s_cbranch_vccnz .LBB0_130
	v_cvt_pk_bf16_f32 v114, v104, v105
	v_cvt_pk_bf16_f32 v115, v106, v107
	global_store_dwordx2 v[154:155], v[114:115], off offset:32
.LBB0_130:
	s_and_b64 vcc, exec, s[6:7]
	v_lshlrev_b32_e32 v116, 16, v174
	v_and_b32_e32 v117, 0xffff0000, v174
	v_lshlrev_b32_e32 v114, 16, v175
	v_and_b32_e32 v115, 0xffff0000, v175
	v_pk_fma_f32 v[102:103], v[102:103], v[136:137], v[114:115]
	v_pk_fma_f32 v[100:101], v[100:101], v[134:135], v[116:117]
	s_cbranch_vccnz .LBB0_132
	v_cvt_pk_bf16_f32 v114, v100, v101
	v_cvt_pk_bf16_f32 v115, v102, v103
	global_store_dwordx2 v[154:155], v[114:115], off offset:256
.LBB0_132:
	s_and_b64 vcc, exec, s[6:7]
	v_lshlrev_b32_e32 v116, 16, v176
	v_and_b32_e32 v117, 0xffff0000, v176
	v_lshlrev_b32_e32 v114, 16, v177
	v_and_b32_e32 v115, 0xffff0000, v177
	v_pk_fma_f32 v[94:95], v[94:95], v[132:133], v[114:115]
	v_pk_fma_f32 v[92:93], v[92:93], v[130:131], v[116:117]
	s_cbranch_vccnz .LBB0_134
	v_cvt_pk_bf16_f32 v114, v92, v93
	v_cvt_pk_bf16_f32 v115, v94, v95
	global_store_dwordx2 v[154:155], v[114:115], off offset:288
.LBB0_134:
	v_or_b32_e32 v114, 32, v152
	v_ashrrev_i32_e32 v115, 31, v114
	v_lshlrev_b64 v[114:115], 11, v[114:115]
	v_lshl_add_u64 v[114:115], s[12:13], 0, v[114:115]
	v_lshl_add_u64 v[114:115], v[146:147], 1, v[114:115]
	s_and_b64 vcc, exec, s[6:7]
	v_lshlrev_b32_e32 v154, 16, v178
	v_and_b32_e32 v155, 0xffff0000, v178
	v_lshlrev_b32_e32 v116, 16, v179
	v_and_b32_e32 v117, 0xffff0000, v179
	v_pk_fma_f32 v[98:99], v[98:99], v[144:145], v[116:117]
	v_pk_fma_f32 v[96:97], v[96:97], v[142:143], v[154:155]
	s_cbranch_vccnz .LBB0_136
	v_cvt_pk_bf16_f32 v116, v96, v97
	v_cvt_pk_bf16_f32 v117, v98, v99
	global_store_dwordx2 v[114:115], v[116:117], off
.LBB0_136:
	s_and_b64 vcc, exec, s[6:7]
	v_lshlrev_b32_e32 v154, 16, v180
	v_and_b32_e32 v155, 0xffff0000, v180
	v_lshlrev_b32_e32 v116, 16, v181
	v_and_b32_e32 v117, 0xffff0000, v181
	v_pk_fma_f32 v[90:91], v[90:91], v[140:141], v[116:117]
	v_pk_fma_f32 v[88:89], v[88:89], v[138:139], v[154:155]
	s_cbranch_vccnz .LBB0_138
	v_cvt_pk_bf16_f32 v116, v88, v89
	v_cvt_pk_bf16_f32 v117, v90, v91
	global_store_dwordx2 v[114:115], v[116:117], off offset:32
.LBB0_138:
	s_and_b64 vcc, exec, s[6:7]
	v_lshlrev_b32_e32 v154, 16, v182
	v_and_b32_e32 v155, 0xffff0000, v182
	v_lshlrev_b32_e32 v116, 16, v183
	v_and_b32_e32 v117, 0xffff0000, v183
	v_pk_fma_f32 v[86:87], v[86:87], v[136:137], v[116:117]
	v_pk_fma_f32 v[84:85], v[84:85], v[134:135], v[154:155]
	s_cbranch_vccnz .LBB0_140
	v_cvt_pk_bf16_f32 v116, v84, v85
	v_cvt_pk_bf16_f32 v117, v86, v87
	global_store_dwordx2 v[114:115], v[116:117], off offset:256
.LBB0_140:
	s_and_b64 vcc, exec, s[6:7]
	v_lshlrev_b32_e32 v154, 16, v184
	v_and_b32_e32 v155, 0xffff0000, v184
	v_lshlrev_b32_e32 v116, 16, v185
	v_and_b32_e32 v117, 0xffff0000, v185
	v_pk_fma_f32 v[78:79], v[78:79], v[132:133], v[116:117]
	v_pk_fma_f32 v[76:77], v[76:77], v[130:131], v[154:155]
	s_cbranch_vccnz .LBB0_142
	v_cvt_pk_bf16_f32 v116, v76, v77
	v_cvt_pk_bf16_f32 v117, v78, v79
	global_store_dwordx2 v[114:115], v[116:117], off offset:288
.LBB0_142:
	v_or_b32_e32 v114, 48, v152
	v_ashrrev_i32_e32 v115, 31, v114
	v_lshlrev_b64 v[114:115], 11, v[114:115]
	v_lshl_add_u64 v[114:115], s[12:13], 0, v[114:115]
	v_lshl_add_u64 v[114:115], v[146:147], 1, v[114:115]
	s_and_b64 vcc, exec, s[6:7]
	v_lshlrev_b32_e32 v154, 16, v190
	v_and_b32_e32 v155, 0xffff0000, v190
	v_lshlrev_b32_e32 v116, 16, v191
	v_and_b32_e32 v117, 0xffff0000, v191
	v_pk_fma_f32 v[82:83], v[82:83], v[144:145], v[116:117]
	v_pk_fma_f32 v[80:81], v[80:81], v[142:143], v[154:155]
	s_cbranch_vccnz .LBB0_144
	v_cvt_pk_bf16_f32 v116, v80, v81
	v_cvt_pk_bf16_f32 v117, v82, v83
	global_store_dwordx2 v[114:115], v[116:117], off
.LBB0_144:
	s_and_b64 vcc, exec, s[6:7]
	v_lshlrev_b32_e32 v154, 16, v214
	v_and_b32_e32 v155, 0xffff0000, v214
	v_lshlrev_b32_e32 v116, 16, v215
	v_and_b32_e32 v117, 0xffff0000, v215
	v_pk_fma_f32 v[74:75], v[74:75], v[140:141], v[116:117]
	v_pk_fma_f32 v[72:73], v[72:73], v[138:139], v[154:155]
	s_cbranch_vccnz .LBB0_146
	v_cvt_pk_bf16_f32 v116, v72, v73
	v_cvt_pk_bf16_f32 v117, v74, v75
	global_store_dwordx2 v[114:115], v[116:117], off offset:32
.LBB0_146:
	s_and_b64 vcc, exec, s[6:7]
	v_lshlrev_b32_e32 v154, 16, v216
	v_and_b32_e32 v155, 0xffff0000, v216
	v_lshlrev_b32_e32 v116, 16, v217
	v_and_b32_e32 v117, 0xffff0000, v217
	v_pk_fma_f32 v[70:71], v[70:71], v[136:137], v[116:117]
	v_pk_fma_f32 v[68:69], v[68:69], v[134:135], v[154:155]
	s_cbranch_vccnz .LBB0_148
	v_cvt_pk_bf16_f32 v116, v68, v69
	v_cvt_pk_bf16_f32 v117, v70, v71
	global_store_dwordx2 v[114:115], v[116:117], off offset:256
.LBB0_148:
	s_and_b64 vcc, exec, s[6:7]
	v_lshlrev_b32_e32 v154, 16, v218
	v_and_b32_e32 v155, 0xffff0000, v218
	v_lshlrev_b32_e32 v116, 16, v219
	v_and_b32_e32 v117, 0xffff0000, v219
	v_pk_fma_f32 v[66:67], v[66:67], v[132:133], v[116:117]
	v_pk_fma_f32 v[64:65], v[64:65], v[130:131], v[154:155]
	s_cbranch_vccnz .LBB0_150
	v_cvt_pk_bf16_f32 v116, v64, v65
	v_cvt_pk_bf16_f32 v117, v66, v67
	global_store_dwordx2 v[114:115], v[116:117], off offset:288
.LBB0_150:
	v_lshlrev_b64 v[114:115], 11, v[152:153]
	v_lshl_add_u64 v[114:115], s[12:13], 0, v[114:115]
	v_lshl_add_u64 v[114:115], v[146:147], 1, v[114:115]
	v_add_co_u32_e32 v116, vcc, 0x40000, v114
	s_mov_b64 s[0:1], 0x40000
	s_nop 0
	v_addc_co_u32_e32 v117, vcc, 0, v115, vcc
	v_lshl_add_u64 v[114:115], v[114:115], 0, s[0:1]
	s_and_b64 vcc, exec, s[6:7]
	v_lshlrev_b32_e32 v154, 16, v220
	v_and_b32_e32 v155, 0xffff0000, v220
	v_lshlrev_b32_e32 v116, 16, v221
	v_and_b32_e32 v117, 0xffff0000, v221
	v_pk_fma_f32 v[62:63], v[62:63], v[144:145], v[116:117]
	v_pk_fma_f32 v[60:61], v[60:61], v[142:143], v[154:155]
	s_cbranch_vccnz .LBB0_152
	v_cvt_pk_bf16_f32 v116, v60, v61
	v_cvt_pk_bf16_f32 v117, v62, v63
	global_store_dwordx2 v[114:115], v[116:117], off
.LBB0_152:
	s_and_b64 vcc, exec, s[6:7]
	v_lshlrev_b32_e32 v154, 16, v222
	v_and_b32_e32 v155, 0xffff0000, v222
	v_lshlrev_b32_e32 v116, 16, v223
	v_and_b32_e32 v117, 0xffff0000, v223
	v_pk_fma_f32 v[58:59], v[58:59], v[140:141], v[116:117]
	v_pk_fma_f32 v[56:57], v[56:57], v[138:139], v[154:155]
	s_cbranch_vccnz .LBB0_154
	v_cvt_pk_bf16_f32 v116, v56, v57
	v_cvt_pk_bf16_f32 v117, v58, v59
	global_store_dwordx2 v[114:115], v[116:117], off offset:32
.LBB0_154:
	s_and_b64 vcc, exec, s[6:7]
	v_lshlrev_b32_e32 v154, 16, v224
	v_and_b32_e32 v155, 0xffff0000, v224
	v_lshlrev_b32_e32 v116, 16, v225
	v_and_b32_e32 v117, 0xffff0000, v225
	v_pk_fma_f32 v[54:55], v[54:55], v[136:137], v[116:117]
	v_pk_fma_f32 v[52:53], v[52:53], v[134:135], v[154:155]
	s_cbranch_vccnz .LBB0_156
	v_cvt_pk_bf16_f32 v116, v52, v53
	v_cvt_pk_bf16_f32 v117, v54, v55
	global_store_dwordx2 v[114:115], v[116:117], off offset:256
.LBB0_156:
	s_and_b64 vcc, exec, s[6:7]
	v_lshlrev_b32_e32 v154, 16, v226
	v_and_b32_e32 v155, 0xffff0000, v226
	v_lshlrev_b32_e32 v116, 16, v227
	v_and_b32_e32 v117, 0xffff0000, v227
	v_pk_fma_f32 v[46:47], v[46:47], v[132:133], v[116:117]
	v_pk_fma_f32 v[44:45], v[44:45], v[130:131], v[154:155]
	s_cbranch_vccnz .LBB0_158
	v_cvt_pk_bf16_f32 v116, v44, v45
	v_cvt_pk_bf16_f32 v117, v46, v47
	global_store_dwordx2 v[114:115], v[116:117], off offset:288
.LBB0_158:
	v_lshlrev_b64 v[114:115], 11, v[152:153]
	v_lshl_add_u64 v[114:115], s[12:13], 0, v[114:115]
	v_lshl_add_u64 v[114:115], v[146:147], 1, v[114:115]
	v_add_co_u32_e32 v116, vcc, 0x48000, v114
	s_mov_b64 s[0:1], 0x48000
	s_nop 0
	v_addc_co_u32_e32 v117, vcc, 0, v115, vcc
	v_lshl_add_u64 v[114:115], v[114:115], 0, s[0:1]
	s_and_b64 vcc, exec, s[6:7]
	v_lshlrev_b32_e32 v154, 16, v228
	v_and_b32_e32 v155, 0xffff0000, v228
	v_lshlrev_b32_e32 v116, 16, v229
	v_and_b32_e32 v117, 0xffff0000, v229
	v_pk_fma_f32 v[50:51], v[50:51], v[144:145], v[116:117]
	v_pk_fma_f32 v[48:49], v[48:49], v[142:143], v[154:155]
	s_cbranch_vccnz .LBB0_160
	v_cvt_pk_bf16_f32 v116, v48, v49
	v_cvt_pk_bf16_f32 v117, v50, v51
	global_store_dwordx2 v[114:115], v[116:117], off
.LBB0_160:
	s_and_b64 vcc, exec, s[6:7]
	v_lshlrev_b32_e32 v154, 16, v230
	v_and_b32_e32 v155, 0xffff0000, v230
	v_lshlrev_b32_e32 v116, 16, v231
	v_and_b32_e32 v117, 0xffff0000, v231
	v_pk_fma_f32 v[42:43], v[42:43], v[140:141], v[116:117]
	v_pk_fma_f32 v[40:41], v[40:41], v[138:139], v[154:155]
	s_cbranch_vccnz .LBB0_162
	v_cvt_pk_bf16_f32 v116, v40, v41
	v_cvt_pk_bf16_f32 v117, v42, v43
	global_store_dwordx2 v[114:115], v[116:117], off offset:32
.LBB0_162:
	s_and_b64 vcc, exec, s[6:7]
	v_lshlrev_b32_e32 v154, 16, v232
	v_and_b32_e32 v155, 0xffff0000, v232
	v_lshlrev_b32_e32 v116, 16, v233
	v_and_b32_e32 v117, 0xffff0000, v233
	v_pk_fma_f32 v[38:39], v[38:39], v[136:137], v[116:117]
	v_pk_fma_f32 v[36:37], v[36:37], v[134:135], v[154:155]
	s_cbranch_vccnz .LBB0_164
	v_cvt_pk_bf16_f32 v116, v36, v37
	v_cvt_pk_bf16_f32 v117, v38, v39
	global_store_dwordx2 v[114:115], v[116:117], off offset:256
.LBB0_164:
	s_and_b64 vcc, exec, s[6:7]
	v_lshlrev_b32_e32 v154, 16, v234
	v_and_b32_e32 v155, 0xffff0000, v234
	v_lshlrev_b32_e32 v116, 16, v235
	v_and_b32_e32 v117, 0xffff0000, v235
	v_pk_fma_f32 v[30:31], v[30:31], v[132:133], v[116:117]
	v_pk_fma_f32 v[28:29], v[28:29], v[130:131], v[154:155]
	s_cbranch_vccnz .LBB0_166
	v_cvt_pk_bf16_f32 v116, v28, v29
	v_cvt_pk_bf16_f32 v117, v30, v31
	global_store_dwordx2 v[114:115], v[116:117], off offset:288
.LBB0_166:
	v_lshlrev_b64 v[114:115], 11, v[152:153]
	v_lshl_add_u64 v[114:115], s[12:13], 0, v[114:115]
	v_lshl_add_u64 v[114:115], v[146:147], 1, v[114:115]
	v_add_co_u32_e32 v116, vcc, 0x50000, v114
	s_mov_b64 s[0:1], 0x50000
	s_nop 0
	v_addc_co_u32_e32 v117, vcc, 0, v115, vcc
	v_lshl_add_u64 v[154:155], v[114:115], 0, s[0:1]
	s_and_b64 vcc, exec, s[6:7]
	v_lshlrev_b32_e32 v114, 16, v236
	v_and_b32_e32 v115, 0xffff0000, v236
	v_lshlrev_b32_e32 v116, 16, v237
	v_and_b32_e32 v117, 0xffff0000, v237
	v_pk_fma_f32 v[34:35], v[34:35], v[144:145], v[116:117]
	v_pk_fma_f32 v[32:33], v[32:33], v[142:143], v[114:115]
	s_cbranch_vccnz .LBB0_168
	v_cvt_pk_bf16_f32 v114, v32, v33
	v_cvt_pk_bf16_f32 v115, v34, v35
	global_store_dwordx2 v[154:155], v[114:115], off
.LBB0_168:
	s_and_b64 vcc, exec, s[6:7]
	v_lshlrev_b32_e32 v116, 16, v238
	v_and_b32_e32 v117, 0xffff0000, v238
	v_lshlrev_b32_e32 v114, 16, v239
	v_and_b32_e32 v115, 0xffff0000, v239
	v_pk_fma_f32 v[26:27], v[26:27], v[140:141], v[114:115]
	v_pk_fma_f32 v[24:25], v[24:25], v[138:139], v[116:117]
	s_cbranch_vccnz .LBB0_170
	v_cvt_pk_bf16_f32 v114, v24, v25
	v_cvt_pk_bf16_f32 v115, v26, v27
	global_store_dwordx2 v[154:155], v[114:115], off offset:32
.LBB0_170:
	s_and_b64 vcc, exec, s[6:7]
	v_lshlrev_b32_e32 v116, 16, v240
	v_and_b32_e32 v117, 0xffff0000, v240
	v_lshlrev_b32_e32 v114, 16, v241
	v_and_b32_e32 v115, 0xffff0000, v241
	v_pk_fma_f32 v[22:23], v[22:23], v[136:137], v[114:115]
	v_pk_fma_f32 v[20:21], v[20:21], v[134:135], v[116:117]
	s_cbranch_vccnz .LBB0_172
	v_cvt_pk_bf16_f32 v114, v20, v21
	v_cvt_pk_bf16_f32 v115, v22, v23
	global_store_dwordx2 v[154:155], v[114:115], off offset:256
.LBB0_172:
	s_and_b64 vcc, exec, s[6:7]
	v_lshlrev_b32_e32 v116, 16, v242
	v_and_b32_e32 v117, 0xffff0000, v242
	v_lshlrev_b32_e32 v114, 16, v243
	v_and_b32_e32 v115, 0xffff0000, v243
	v_pk_fma_f32 v[114:115], v[14:15], v[132:133], v[114:115]
	v_pk_fma_f32 v[116:117], v[12:13], v[130:131], v[116:117]
	s_cbranch_vccnz .LBB0_174
	v_cvt_pk_bf16_f32 v12, v116, v117
	v_cvt_pk_bf16_f32 v13, v114, v115
	global_store_dwordx2 v[154:155], v[12:13], off offset:288
.LBB0_174:
	v_lshlrev_b64 v[12:13], 11, v[152:153]
	v_lshl_add_u64 v[12:13], s[12:13], 0, v[12:13]
	v_lshl_add_u64 v[12:13], v[146:147], 1, v[12:13]
	v_add_co_u32_e32 v14, vcc, 0x58000, v12
	s_mov_b64 s[0:1], 0x58000
	s_nop 0
	v_addc_co_u32_e32 v15, vcc, 0, v13, vcc
	v_lshl_add_u64 v[12:13], v[12:13], 0, s[0:1]
	s_and_b64 vcc, exec, s[6:7]
	v_lshlrev_b32_e32 v152, 16, v244
	v_and_b32_e32 v153, 0xffff0000, v244
	v_lshlrev_b32_e32 v14, 16, v245
	v_and_b32_e32 v15, 0xffff0000, v245
	v_pk_fma_f32 v[18:19], v[18:19], v[144:145], v[14:15]
	v_pk_fma_f32 v[16:17], v[16:17], v[142:143], v[152:153]
	s_cbranch_vccnz .LBB0_176
	v_cvt_pk_bf16_f32 v14, v16, v17
	v_cvt_pk_bf16_f32 v15, v18, v19
	global_store_dwordx2 v[12:13], v[14:15], off
.LBB0_176:
	s_and_b64 vcc, exec, s[6:7]
	v_lshlrev_b32_e32 v142, 16, v246
	v_and_b32_e32 v143, 0xffff0000, v246
	v_lshlrev_b32_e32 v14, 16, v247
	v_and_b32_e32 v15, 0xffff0000, v247
	v_pk_fma_f32 v[140:141], v[10:11], v[140:141], v[14:15]
	v_pk_fma_f32 v[138:139], v[8:9], v[138:139], v[142:143]
	s_cbranch_vccnz .LBB0_178
	v_cvt_pk_bf16_f32 v8, v138, v139
	v_cvt_pk_bf16_f32 v9, v140, v141
	global_store_dwordx2 v[12:13], v[8:9], off offset:32
.LBB0_178:
	s_and_b64 vcc, exec, s[6:7]
	v_lshlrev_b32_e32 v10, 16, v248
	v_and_b32_e32 v11, 0xffff0000, v248
	v_lshlrev_b32_e32 v8, 16, v249
	v_and_b32_e32 v9, 0xffff0000, v249
	v_pk_fma_f32 v[136:137], v[6:7], v[136:137], v[8:9]
	v_pk_fma_f32 v[134:135], v[4:5], v[134:135], v[10:11]
	s_cbranch_vccnz .LBB0_180
	v_cvt_pk_bf16_f32 v4, v134, v135
	v_cvt_pk_bf16_f32 v5, v136, v137
	global_store_dwordx2 v[12:13], v[4:5], off offset:256
.LBB0_180:
	s_and_b64 vcc, exec, s[6:7]
	v_lshlrev_b32_e32 v6, 16, v250
	v_and_b32_e32 v7, 0xffff0000, v250
	v_lshlrev_b32_e32 v4, 16, v251
	v_and_b32_e32 v5, 0xffff0000, v251
	v_pk_fma_f32 v[132:133], v[2:3], v[132:133], v[4:5]
	v_pk_fma_f32 v[130:131], v[0:1], v[130:131], v[6:7]
	s_cbranch_vccnz .LBB0_182
	v_cvt_pk_bf16_f32 v0, v130, v131
	v_cvt_pk_bf16_f32 v1, v132, v133
	global_store_dwordx2 v[12:13], v[0:1], off offset:288
